# hyena filter second hidden layer loop: 16 flt_w2 loads in flight per wait (unrolled x4, same summation order), with LDS-staged flt_w3
# baseline (speedup 1.0000x reference)
.LBB0_380:
	global_load_dword v23, v[16:17], off offset:-512
	global_load_dword v28, v[16:17], off offset:-256
	global_load_dword v29, v[16:17], off
	global_load_dword v30, v[16:17], off offset:256
	global_load_dword v120, v[16:17], off offset:512
	global_load_dword v121, v[16:17], off offset:768
	global_load_dword v122, v[16:17], off offset:1024
	global_load_dword v123, v[16:17], off offset:1280
	global_load_dword v124, v[16:17], off offset:1536
	global_load_dword v125, v[16:17], off offset:1792
	global_load_dword v126, v[16:17], off offset:2048
	global_load_dword v127, v[16:17], off offset:2304
	global_load_dword v128, v[16:17], off offset:2560
	global_load_dword v129, v[16:17], off offset:2816
	global_load_dword v130, v[16:17], off offset:3072
	global_load_dword v131, v[16:17], off offset:3328
	v_add_u32_e32 v132, s8, v2
	ds_read_b128 v[24:27], v132
	ds_read_b128 v[134:137], v132 offset:16
	ds_read_b128 v[138:141], v132 offset:32
	ds_read_b128 v[142:145], v132 offset:48
	s_add_i32 s8, s8, 64
	s_mov_b64 s[10:11], 0x1000
	v_lshl_add_u64 v[16:17], v[16:17], 0, s[10:11]
	s_cmpk_eq_i32 s8, 0x100
	s_waitcnt vmcnt(15) lgkmcnt(0)
	v_fmac_f32_e32 v22, v24, v23
	s_waitcnt vmcnt(14)
	v_fmac_f32_e32 v22, v25, v28
	s_waitcnt vmcnt(13)
	v_fmac_f32_e32 v22, v26, v29
	s_waitcnt vmcnt(12)
	v_fmac_f32_e32 v22, v27, v30
	s_waitcnt vmcnt(11)
	v_fmac_f32_e32 v22, v134, v120
	s_waitcnt vmcnt(10)
	v_fmac_f32_e32 v22, v135, v121
	s_waitcnt vmcnt(9)
	v_fmac_f32_e32 v22, v136, v122
	s_waitcnt vmcnt(8)
	v_fmac_f32_e32 v22, v137, v123
	s_waitcnt vmcnt(7)
	v_fmac_f32_e32 v22, v138, v124
	s_waitcnt vmcnt(6)
	v_fmac_f32_e32 v22, v139, v125
	s_waitcnt vmcnt(5)
	v_fmac_f32_e32 v22, v140, v126
	s_waitcnt vmcnt(4)
	v_fmac_f32_e32 v22, v141, v127
	s_waitcnt vmcnt(3)
	v_fmac_f32_e32 v22, v142, v128
	s_waitcnt vmcnt(2)
	v_fmac_f32_e32 v22, v143, v129
	s_waitcnt vmcnt(1)
	v_fmac_f32_e32 v22, v144, v130
	s_waitcnt vmcnt(0)
	v_fmac_f32_e32 v22, v145, v131
	s_cbranch_scc0 .LBB0_380
	v_mul_f32_e32 v16, v19, v22
	v_and_b32_e32 v17, 0x7fffffff, v16
	v_cmp_nlt_f32_e64 s[8:9], |v16|, s50
	s_and_saveexec_b64 s[10:11], s[8:9]
	s_xor_b64 s[28:29], exec, s[10:11]
	s_cbranch_execz .LBB0_383
	v_lshrrev_b32_e32 v2, 23, v17
	v_add_u32_e32 v2, 0xffffff88, v2
	v_cmp_lt_u32_e32 vcc, 63, v2
	s_nop 1
	v_cndmask_b32_e32 v22, 0, v43, vcc
	v_add_u32_e32 v2, v22, v2
	v_cmp_lt_u32_e64 s[8:9], 31, v2
	s_nop 1
	v_cndmask_b32_e64 v22, 0, v44, s[8:9]
	v_add_u32_e32 v2, v22, v2
	v_cmp_lt_u32_e64 s[10:11], 31, v2
	s_nop 1
	v_cndmask_b32_e64 v22, 0, v44, s[10:11]
	v_add_u32_e32 v47, v22, v2
	v_and_b32_e32 v2, 0x7fffff, v17
	v_or_b32_e32 v34, 0x800000, v2
	v_mad_u64_u32 v[22:23], s[12:13], v34, s51, 0
	v_mov_b32_e32 v2, v23
	v_mad_u64_u32 v[24:25], s[12:13], v34, s56, v[2:3]
	v_mov_b32_e32 v2, v25
	v_mad_u64_u32 v[26:27], s[12:13], v34, s57, v[2:3]
	v_mov_b32_e32 v2, v27
	v_mad_u64_u32 v[28:29], s[12:13], v34, s58, v[2:3]
	v_mov_b32_e32 v2, v29
	v_mad_u64_u32 v[30:31], s[12:13], v34, s59, v[2:3]
	v_mov_b32_e32 v2, v31
	v_mad_u64_u32 v[32:33], s[12:13], v34, s60, v[2:3]
	v_mov_b32_e32 v2, v33
	v_mad_u64_u32 v[34:35], s[12:13], v34, s61, v[2:3]
	v_cndmask_b32_e32 v23, v32, v28, vcc
	v_cndmask_b32_e32 v2, v34, v30, vcc
	v_cndmask_b32_e32 v27, v35, v32, vcc
	v_cndmask_b32_e64 v25, v2, v23, s[8:9]
	v_cndmask_b32_e64 v2, v27, v2, s[8:9]
	v_cndmask_b32_e32 v27, v30, v26, vcc
	v_cndmask_b32_e64 v23, v23, v27, s[8:9]
	v_cndmask_b32_e32 v24, v28, v24, vcc
	v_cndmask_b32_e64 v2, v2, v25, s[10:11]
	v_cndmask_b32_e64 v25, v25, v23, s[10:11]
	v_sub_u32_e32 v29, 32, v47
	v_cndmask_b32_e64 v27, v27, v24, s[8:9]
	v_alignbit_b32 v30, v2, v25, v29
	v_cmp_eq_u32_e64 s[12:13], 0, v47
	v_cndmask_b32_e64 v23, v23, v27, s[10:11]
	v_cndmask_b32_e32 v22, v26, v22, vcc
	v_cndmask_b32_e64 v2, v30, v2, s[12:13]
	v_alignbit_b32 v28, v25, v23, v29
	v_cndmask_b32_e64 v22, v24, v22, s[8:9]
	v_cndmask_b32_e64 v25, v28, v25, s[12:13]
	v_bfe_u32 v31, v2, 29, 1
	v_cndmask_b32_e64 v22, v27, v22, s[10:11]
	v_alignbit_b32 v28, v2, v25, 30
	v_sub_u32_e32 v32, 0, v31
	v_alignbit_b32 v24, v23, v22, v29
	v_xor_b32_e32 v28, v28, v32
	v_cndmask_b32_e64 v23, v24, v23, s[12:13]
	v_alignbit_b32 v24, v25, v23, 30
	v_ffbh_u32_e32 v25, v28
	v_min_u32_e32 v25, 32, v25
	v_alignbit_b32 v22, v23, v22, 30
	v_xor_b32_e32 v24, v24, v32
	v_sub_u32_e32 v26, 31, v25
	v_xor_b32_e32 v22, v22, v32
	v_alignbit_b32 v27, v28, v24, v26
	v_alignbit_b32 v22, v24, v22, v26
	v_alignbit_b32 v23, v27, v22, 9
	v_ffbh_u32_e32 v24, v23
	v_min_u32_e32 v24, 32, v24
	v_lshrrev_b32_e32 v30, 29, v2
	v_not_b32_e32 v26, v24
	v_alignbit_b32 v22, v23, v22, v26
	v_lshlrev_b32_e32 v23, 31, v30
	v_or_b32_e32 v26, 0x33000000, v23
	v_add_lshl_u32 v24, v24, v25, 23
	v_lshrrev_b32_e32 v22, 9, v22
	v_sub_u32_e32 v24, v26, v24
	v_or_b32_e32 v23, 0.5, v23
	v_lshlrev_b32_e32 v25, 23, v25
	v_or_b32_e32 v22, v24, v22
	v_lshrrev_b32_e32 v24, 9, v27
	v_sub_u32_e32 v23, v23, v25
	v_or_b32_e32 v23, v24, v23
	v_mul_f32_e32 v24, 0x3fc90fda, v23
	v_fma_f32 v25, v23, s62, -v24
	v_fmac_f32_e32 v25, 0x33a22168, v23
	v_fmac_f32_e32 v25, 0x3fc90fda, v22
	v_lshrrev_b32_e32 v2, 30, v2
	v_add_f32_e32 v22, v24, v25
	v_add_u32_e32 v2, v31, v2
